# code placement: hgB step loop, attention, retA and hgA loop heads pinned to 8-byte alignment (hgB was at 4 mod 8)
# speedup vs baseline: 1.0060x; 1.0060x over previous
.LBB0_195:
	s_add_i32 s88, s88, -1
	v_pk_mul_f32 v[2:3], v[98:99], v[2:3]
	v_pk_mul_f32 v[0:1], v[96:97], v[0:1]
	v_pk_mul_f32 v[6:7], v[98:99], v[6:7]
	v_pk_mul_f32 v[4:5], v[96:97], v[4:5]
	v_pk_mul_f32 v[10:11], v[98:99], v[10:11]
	v_pk_mul_f32 v[8:9], v[96:97], v[8:9]
	v_pk_mul_f32 v[14:15], v[98:99], v[14:15]
	v_pk_mul_f32 v[12:13], v[96:97], v[12:13]
	v_pk_mul_f32 v[18:19], v[102:103], v[18:19]
	v_pk_mul_f32 v[16:17], v[100:101], v[16:17]
	v_pk_mul_f32 v[22:23], v[102:103], v[22:23]
	v_pk_mul_f32 v[20:21], v[100:101], v[20:21]
	v_pk_mul_f32 v[34:35], v[102:103], v[34:35]
	v_pk_mul_f32 v[32:33], v[100:101], v[32:33]
	v_pk_mul_f32 v[38:39], v[102:103], v[38:39]
	v_pk_mul_f32 v[36:37], v[100:101], v[36:37]
	v_pk_mul_f32 v[26:27], v[110:111], v[26:27]
	v_pk_mul_f32 v[24:25], v[108:109], v[24:25]
	v_pk_mul_f32 v[30:31], v[110:111], v[30:31]
	v_pk_mul_f32 v[28:29], v[108:109], v[28:29]
	v_pk_mul_f32 v[42:43], v[110:111], v[42:43]
	v_pk_mul_f32 v[40:41], v[108:109], v[40:41]
	v_pk_mul_f32 v[46:47], v[110:111], v[46:47]
	v_pk_mul_f32 v[44:45], v[108:109], v[44:45]
	s_waitcnt lgkmcnt(0)
	v_pk_mul_f32 v[50:51], v[106:107], v[50:51]
	v_pk_mul_f32 v[48:49], v[104:105], v[48:49]
	v_pk_mul_f32 v[54:55], v[106:107], v[54:55]
	v_pk_mul_f32 v[52:53], v[104:105], v[52:53]
	v_pk_mul_f32 v[58:59], v[106:107], v[58:59]
	v_pk_mul_f32 v[56:57], v[104:105], v[56:57]
	v_pk_mul_f32 v[62:63], v[106:107], v[62:63]
	v_pk_mul_f32 v[60:61], v[104:105], v[60:61]
	v_add_u32_e32 v186, 0x200, v186
	v_xor_b32_e32 v237, 0x1000, v237
	s_cmp_lg_u32 s88, -2
	s_mov_b32 s91, s53
	s_cbranch_scc0 .LBB0_190
	.p2align	3

.LBB0_249:
	s_or_b64 exec, exec, s[2:3]
	s_add_i32 s26, s26, s21
	s_waitcnt vmcnt(9)
	v_mov_b64_e32 v[94:95], v[46:47]
	s_waitcnt vmcnt(8)
	v_mov_b64_e32 v[74:75], v[26:27]
	v_mov_b64_e32 v[82:83], v[34:35]
	v_mov_b64_e32 v[78:79], v[30:31]
	v_mov_b64_e32 v[86:87], v[38:39]
	v_mov_b64_e32 v[90:91], v[42:43]
	v_mov_b64_e32 v[66:67], v[18:19]
	v_mov_b64_e32 v[70:71], v[22:23]
	s_cmpk_lt_i32 s27, 0x120
	v_mov_b64_e32 v[92:93], v[44:45]
	v_mov_b64_e32 v[72:73], v[24:25]
	v_mov_b64_e32 v[80:81], v[32:33]
	v_mov_b64_e32 v[76:77], v[28:29]
	v_mov_b64_e32 v[84:85], v[36:37]
	v_mov_b64_e32 v[88:89], v[40:41]
	v_mov_b64_e32 v[64:65], v[16:17]
	v_mov_b64_e32 v[68:69], v[20:21]
	s_mov_b32 s12, s27
	v_mov_b32_e32 v108, v60
	v_mov_b32_e32 v109, v61
	v_mov_b32_e32 v110, v62
	v_mov_b32_e32 v111, v63
	v_mov_b32_e32 v100, v56
	v_mov_b32_e32 v101, v57
	v_mov_b32_e32 v102, v58
	v_mov_b32_e32 v103, v59
	v_mov_b32_e32 v96, v52
	v_mov_b32_e32 v97, v53
	v_mov_b32_e32 v98, v54
	v_mov_b32_e32 v99, v55
	v_mov_b32_e32 v104, v48
	v_mov_b32_e32 v105, v49
	v_mov_b32_e32 v106, v50
	v_mov_b32_e32 v107, v51
	s_barrier
	s_cbranch_scc0 .LBB0_302
	.p2align	3

.LBB0_304:
	ds_read_b64_tr_b16 v[28:29], v41
	ds_read_b64_tr_b16 v[30:31], v41 offset:576
	ds_read_b64_tr_b16 v[24:25], v41 offset:4608
	ds_read_b64_tr_b16 v[26:27], v41 offset:5184
	ds_read_b64_tr_b16 v[20:21], v41 offset:9216
	ds_read_b64_tr_b16 v[22:23], v41 offset:9792
	ds_read_b64_tr_b16 v[16:17], v41 offset:13824
	ds_read_b64_tr_b16 v[18:19], v41 offset:14400
	ds_read_b64_tr_b16 v[42:43], v40 offset:36864
	ds_read_b64_tr_b16 v[44:45], v40 offset:37440
	ds_read_b64_tr_b16 v[46:47], v40 offset:41472
	ds_read_b64_tr_b16 v[48:49], v40 offset:42048
	s_ashr_i32 s3, s2, 31
	s_lshl_b64 s[2:3], s[2:3], 14
	s_waitcnt lgkmcnt(2)
	v_mfma_f32_16x16x32_bf16 v[42:45], v[28:31], v[42:45], 0
	v_lshl_add_u64 v[50:51], v[32:33], 0, s[2:3]
	s_add_i32 s6, s6, s7
	s_mov_b32 s2, s12
	s_waitcnt lgkmcnt(0)
	v_mfma_f32_16x16x32_bf16 v[42:45], v[24:27], v[46:49], v[42:45]
	ds_read_b64_tr_b16 v[46:47], v40 offset:46080
	ds_read_b64_tr_b16 v[48:49], v40 offset:46656
	s_waitcnt lgkmcnt(0)
	v_mfma_f32_16x16x32_bf16 v[42:45], v[20:23], v[46:49], v[42:45]
	ds_read_b64_tr_b16 v[46:47], v40 offset:50688
	ds_read_b64_tr_b16 v[48:49], v40 offset:51264
	s_waitcnt lgkmcnt(0)
	v_mfma_f32_16x16x32_bf16 v[42:45], v[16:19], v[46:49], v[42:45]
	s_nop 7
	v_cvt_pk_bf16_f32 v34, v42, v43
	v_cvt_pk_bf16_f32 v35, v44, v45
	global_store_dwordx2 v[50:51], v[34:35], off
	ds_read_b64_tr_b16 v[42:43], v40 offset:36896
	ds_read_b64_tr_b16 v[44:45], v40 offset:37472
	ds_read_b64_tr_b16 v[46:47], v40 offset:41504
	ds_read_b64_tr_b16 v[48:49], v40 offset:42080
	s_waitcnt lgkmcnt(2)
	v_mfma_f32_16x16x32_bf16 v[42:45], v[28:31], v[42:45], 0
	s_waitcnt lgkmcnt(0)
	v_mfma_f32_16x16x32_bf16 v[42:45], v[24:27], v[46:49], v[42:45]
	ds_read_b64_tr_b16 v[46:47], v40 offset:46112
	ds_read_b64_tr_b16 v[48:49], v40 offset:46688
	s_waitcnt lgkmcnt(0)
	v_mfma_f32_16x16x32_bf16 v[42:45], v[20:23], v[46:49], v[42:45]
	ds_read_b64_tr_b16 v[46:47], v40 offset:50720
	ds_read_b64_tr_b16 v[48:49], v40 offset:51296
	s_waitcnt lgkmcnt(0)
	v_mfma_f32_16x16x32_bf16 v[42:45], v[16:19], v[46:49], v[42:45]
	s_nop 7
	v_cvt_pk_bf16_f32 v34, v42, v43
	v_cvt_pk_bf16_f32 v35, v44, v45
	global_store_dwordx2 v[50:51], v[34:35], off offset:2048
	ds_read_b64_tr_b16 v[42:43], v40 offset:36928
	ds_read_b64_tr_b16 v[44:45], v40 offset:37504
	ds_read_b64_tr_b16 v[46:47], v40 offset:41536
	ds_read_b64_tr_b16 v[48:49], v40 offset:42112
	s_waitcnt lgkmcnt(2)
	v_mfma_f32_16x16x32_bf16 v[42:45], v[28:31], v[42:45], 0
	v_add_co_u32_e32 v34, vcc, s86, v50
	s_waitcnt lgkmcnt(0)
	v_mfma_f32_16x16x32_bf16 v[42:45], v[24:27], v[46:49], v[42:45]
	ds_read_b64_tr_b16 v[46:47], v40 offset:46144
	ds_read_b64_tr_b16 v[48:49], v40 offset:46720
	v_addc_co_u32_e32 v35, vcc, 0, v51, vcc
	s_waitcnt lgkmcnt(0)
	v_mfma_f32_16x16x32_bf16 v[42:45], v[20:23], v[46:49], v[42:45]
	ds_read_b64_tr_b16 v[46:47], v40 offset:50752
	ds_read_b64_tr_b16 v[48:49], v40 offset:51328
	s_andn2_b64 vcc, exec, s[0:1]
	s_waitcnt lgkmcnt(0)
	v_mfma_f32_16x16x32_bf16 v[42:45], v[16:19], v[46:49], v[42:45]
	s_nop 7
	v_cvt_pk_bf16_f32 v42, v42, v43
	v_cvt_pk_bf16_f32 v43, v44, v45
	global_store_dwordx2 v[34:35], v[42:43], off
	ds_read_b64_tr_b16 v[42:43], v40 offset:36960
	ds_read_b64_tr_b16 v[44:45], v40 offset:37536
	s_waitcnt lgkmcnt(0)
	v_mfma_f32_16x16x32_bf16 v[28:31], v[28:31], v[42:45], 0
	ds_read_b64_tr_b16 v[42:43], v40 offset:41568
	ds_read_b64_tr_b16 v[44:45], v40 offset:42144
	s_waitcnt lgkmcnt(0)
	v_mfma_f32_16x16x32_bf16 v[24:27], v[24:27], v[42:45], v[28:31]
	s_nop 3
	ds_read_b64_tr_b16 v[28:29], v40 offset:46176
	ds_read_b64_tr_b16 v[30:31], v40 offset:46752
	s_waitcnt lgkmcnt(0)
	v_mfma_f32_16x16x32_bf16 v[20:23], v[20:23], v[28:31], v[24:27]
	s_nop 2
	ds_read_b64_tr_b16 v[24:25], v40 offset:50784
	ds_read_b64_tr_b16 v[26:27], v40 offset:51360
	s_waitcnt lgkmcnt(0)
	v_mfma_f32_16x16x32_bf16 v[16:19], v[16:19], v[24:27], v[20:23]
	s_nop 7
	v_cvt_pk_bf16_f32 v16, v16, v17
	v_cvt_pk_bf16_f32 v17, v18, v19
	global_store_dwordx2 v[34:35], v[16:17], off offset:2048
	s_barrier
	s_cbranch_vccz .LBB0_307
	.p2align	3

.LBB0_309:
	s_or_b64 exec, exec, s[0:1]
	v_lshrrev_b32_e32 v26, 4, v5
	s_ashr_i32 s0, s15, 2
	s_lshl_b32 s2, s15, 4
	v_bfe_u32 v0, v4, 2, 2
	s_mul_i32 s1, s0, 0x4800
	s_and_b32 s2, s2, 48
	v_lshl_or_b32 v0, v26, 3, v0
	s_add_i32 s1, s1, 16
	v_mul_u32_u24_e32 v18, 0x90, v0
	s_lshl_b32 s3, s2, 1
	v_lshlrev_b32_e32 v0, 3, v4
	s_add_i32 s3, s3, s1
	v_and_b32_e32 v19, 24, v0
	v_add3_u32 v2, s3, v18, v19
	v_add3_u32 v30, 16, v18, v19
	v_and_b32_e32 v27, 15, v4
	s_waitcnt lgkmcnt(0)
	s_barrier
	ds_read_b64_tr_b16 v[12:13], v2
	ds_read_b64_tr_b16 v[14:15], v2 offset:576
	ds_read_b64_tr_b16 v[8:9], v2 offset:4608
	ds_read_b64_tr_b16 v[10:11], v2 offset:5184
	ds_read_b64_tr_b16 v[4:5], v2 offset:9216
	ds_read_b64_tr_b16 v[6:7], v2 offset:9792
	ds_read_b64_tr_b16 v[0:1], v2 offset:13824
	ds_read_b64_tr_b16 v[2:3], v2 offset:14400
	ds_read_b64_tr_b16 v[18:19], v30 offset:36864
	ds_read_b64_tr_b16 v[20:21], v30 offset:37440
	ds_read_b64_tr_b16 v[22:23], v30 offset:41472
	ds_read_b64_tr_b16 v[24:25], v30 offset:42048
	s_waitcnt lgkmcnt(2)
	v_mfma_f32_16x16x32_bf16 v[18:21], v[12:15], v[18:21], 0
	v_add_u32_e32 v16, s0, v16
	v_ashrrev_i32_e32 v17, 31, v16
	v_readlane_b32 s0, v253, 40
	s_waitcnt lgkmcnt(0)
	v_mfma_f32_16x16x32_bf16 v[18:21], v[8:11], v[22:25], v[18:21]
	ds_read_b64_tr_b16 v[22:23], v30 offset:46080
	ds_read_b64_tr_b16 v[24:25], v30 offset:46656
	v_lshlrev_b64 v[16:17], 19, v[16:17]
	v_readlane_b32 s1, v253, 41
	s_waitcnt lgkmcnt(0)
	v_mfma_f32_16x16x32_bf16 v[18:21], v[4:7], v[22:25], v[18:21]
	ds_read_b64_tr_b16 v[22:23], v30 offset:50688
	ds_read_b64_tr_b16 v[24:25], v30 offset:51264
	v_lshl_add_u64 v[16:17], s[0:1], 0, v[16:17]
	s_lshl_b32 s0, s2, 6
	s_waitcnt lgkmcnt(0)
	v_mfma_f32_16x16x32_bf16 v[22:25], v[0:3], v[22:25], v[18:21]
	s_lshl_b32 s96, s13, 14
	s_nop 1
	v_lshlrev_b32_e32 v18, 8, v26
	v_or3_b32 v20, s0, v18, v27
	v_lshl_add_u64 v[16:17], v[16:17], 0, s[96:97]
	v_lshlrev_b32_e32 v128, 2, v20
	v_lshl_add_u64 v[18:19], v[16:17], 0, v[128:129]
	global_store_dword v[18:19], v22, off
	global_store_dword v[18:19], v23, off offset:256
	global_store_dword v[18:19], v24, off offset:512
	global_store_dword v[18:19], v25, off offset:768
	ds_read_b64_tr_b16 v[22:23], v30 offset:36896
	ds_read_b64_tr_b16 v[24:25], v30 offset:37472
	ds_read_b64_tr_b16 v[26:27], v30 offset:41504
	ds_read_b64_tr_b16 v[28:29], v30 offset:42080
	s_waitcnt lgkmcnt(2)
	v_mfma_f32_16x16x32_bf16 v[22:25], v[12:15], v[22:25], 0
	v_or_b32_e32 v128, 16, v20
	s_add_i32 s12, s12, s16
	s_add_i32 s7, s7, s6
	s_waitcnt lgkmcnt(0)
	v_mfma_f32_16x16x32_bf16 v[22:25], v[8:11], v[26:29], v[22:25]
	ds_read_b64_tr_b16 v[26:27], v30 offset:46112
	ds_read_b64_tr_b16 v[28:29], v30 offset:46688
	s_cmpk_gt_i32 s12, 0x3ff
	s_waitcnt lgkmcnt(0)
	v_mfma_f32_16x16x32_bf16 v[22:25], v[4:7], v[26:29], v[22:25]
	ds_read_b64_tr_b16 v[26:27], v30 offset:50720
	ds_read_b64_tr_b16 v[28:29], v30 offset:51296
	s_waitcnt lgkmcnt(0)
	v_mfma_f32_16x16x32_bf16 v[22:25], v[0:3], v[26:29], v[22:25]
	v_lshl_add_u64 v[26:27], v[128:129], 2, v[16:17]
	v_or_b32_e32 v128, 32, v20
	s_nop 5
	global_store_dword v[18:19], v22, off offset:64
	global_store_dword v[26:27], v23, off offset:256
	global_store_dword v[26:27], v24, off offset:512
	global_store_dword v[26:27], v25, off offset:768
	ds_read_b64_tr_b16 v[22:23], v30 offset:36928
	ds_read_b64_tr_b16 v[24:25], v30 offset:37504
	ds_read_b64_tr_b16 v[26:27], v30 offset:41536
	ds_read_b64_tr_b16 v[28:29], v30 offset:42112
	s_waitcnt lgkmcnt(2)
	v_mfma_f32_16x16x32_bf16 v[22:25], v[12:15], v[22:25], 0
	s_waitcnt lgkmcnt(0)
	v_mfma_f32_16x16x32_bf16 v[22:25], v[8:11], v[26:29], v[22:25]
	ds_read_b64_tr_b16 v[26:27], v30 offset:46144
	ds_read_b64_tr_b16 v[28:29], v30 offset:46720
	s_waitcnt lgkmcnt(0)
	v_mfma_f32_16x16x32_bf16 v[22:25], v[4:7], v[26:29], v[22:25]
	ds_read_b64_tr_b16 v[26:27], v30 offset:50752
	ds_read_b64_tr_b16 v[28:29], v30 offset:51328
	s_waitcnt lgkmcnt(0)
	v_mfma_f32_16x16x32_bf16 v[22:25], v[0:3], v[26:29], v[22:25]
	v_lshl_add_u64 v[26:27], v[128:129], 2, v[16:17]
	v_or_b32_e32 v128, 48, v20
	s_nop 5
	global_store_dword v[18:19], v22, off offset:128
	global_store_dword v[26:27], v23, off offset:256
	global_store_dword v[26:27], v24, off offset:512
	global_store_dword v[26:27], v25, off offset:768
	ds_read_b64_tr_b16 v[22:23], v30 offset:36960
	ds_read_b64_tr_b16 v[24:25], v30 offset:37536
	s_waitcnt lgkmcnt(0)
	v_mfma_f32_16x16x32_bf16 v[12:15], v[12:15], v[22:25], 0
	ds_read_b64_tr_b16 v[22:23], v30 offset:41568
	ds_read_b64_tr_b16 v[24:25], v30 offset:42144
	s_waitcnt lgkmcnt(0)
	v_mfma_f32_16x16x32_bf16 v[8:11], v[8:11], v[22:25], v[12:15]
	s_nop 3
	ds_read_b64_tr_b16 v[12:13], v30 offset:46176
	ds_read_b64_tr_b16 v[14:15], v30 offset:46752
	s_waitcnt lgkmcnt(0)
	v_mfma_f32_16x16x32_bf16 v[4:7], v[4:7], v[12:15], v[8:11]
	s_nop 2
	ds_read_b64_tr_b16 v[8:9], v30 offset:50784
	ds_read_b64_tr_b16 v[10:11], v30 offset:51360
	s_waitcnt lgkmcnt(0)
	v_mfma_f32_16x16x32_bf16 v[0:3], v[0:3], v[8:11], v[4:7]
	s_nop 2
	v_lshl_add_u64 v[4:5], v[128:129], 2, v[16:17]
	s_nop 3
	global_store_dword v[18:19], v0, off offset:192
	global_store_dword v[4:5], v1, off offset:256
	global_store_dword v[4:5], v2, off offset:512
	global_store_dword v[4:5], v3, off offset:768
	s_barrier
	s_cbranch_scc1 .LBB0_318
	.p2align	3
